# attention preamble: all four lambda parameters and the two sub_norm vectors requested in one round instead of three
# speedup vs baseline: 1.0106x; 1.0106x over previous
.LBB0_1003:
	s_waitcnt lgkmcnt(0)
	v_mov_b32_e32 v0, s70
	v_mov_b32_e32 v1, s71
	s_barrier
	v_mbcnt_lo_u32_b32 v2, -1, 0
	v_mbcnt_hi_u32_b32 v2, -1, v2
	v_readlane_b32 s0, v241, 4
	v_ashrrev_i32_e32 v3, 31, v2
	v_lshl_add_u64 v[0:1], v[2:3], 2, v[0:1]
	v_readlane_b32 s4, v242, 0
	v_readlane_b32 s5, v242, 1
	s_nop 0
	v_mov_b32_e32 v10, s4
	v_mov_b32_e32 v11, s5
	v_lshl_add_u64 v[10:11], v[2:3], 2, v[10:11]
	global_load_dword v2, v[0:1], off
	global_load_dword v3, v[0:1], off offset:256
	global_load_dword v8, v[0:1], off offset:512
	global_load_dword v9, v[0:1], off offset:768
	global_load_dword v12, v[10:11], off
	global_load_dword v13, v[10:11], off offset:256
	s_cmp_gt_u32 s0, 63
	s_waitcnt vmcnt(2)
	v_mul_f32_e32 v4, v2, v3
	ds_bpermute_b32 v4, v195, v4
	s_waitcnt lgkmcnt(0)
	v_fmac_f32_e32 v4, v2, v3
	ds_bpermute_b32 v2, v196, v4
	s_waitcnt lgkmcnt(0)
	v_add_f32_e32 v2, v4, v2
	v_mov_b32_e32 v4, v8
	s_nop 0
	v_mov_b32_e32 v0, v9
	ds_bpermute_b32 v3, v197, v2
	s_waitcnt lgkmcnt(0)
	v_add_f32_e32 v2, v2, v3
	ds_bpermute_b32 v3, v161, v2
	s_waitcnt lgkmcnt(0)
	v_add_f32_e32 v2, v2, v3
	v_xor_b32_e32 v3, 16, v159
	v_cmp_lt_i32_e32 vcc, v3, v160
	s_waitcnt vmcnt(0)
	v_mul_f32_e32 v1, v4, v0
	ds_bpermute_b32 v1, v195, v1
	v_cndmask_b32_e32 v3, v159, v3, vcc
	v_lshlrev_b32_e32 v198, 2, v3
	ds_bpermute_b32 v3, v198, v2
	s_waitcnt lgkmcnt(1)
	v_fmac_f32_e32 v1, v4, v0
	ds_bpermute_b32 v0, v196, v1
	s_waitcnt lgkmcnt(1)
	v_add_f32_e32 v2, v2, v3
	v_xor_b32_e32 v3, 32, v159
	v_cmp_lt_i32_e32 vcc, v3, v160
	s_waitcnt lgkmcnt(0)
	v_add_f32_e32 v0, v1, v0
	ds_bpermute_b32 v1, v197, v0
	v_cndmask_b32_e32 v3, v159, v3, vcc
	v_lshlrev_b32_e32 v199, 2, v3
	ds_bpermute_b32 v3, v199, v2
	s_waitcnt lgkmcnt(1)
	v_add_f32_e32 v0, v0, v1
	ds_bpermute_b32 v1, v161, v0
	s_waitcnt lgkmcnt(0)
	v_add_f32_e32 v0, v0, v1
	ds_bpermute_b32 v1, v198, v0
	s_waitcnt lgkmcnt(0)
	v_add_f32_e32 v4, v0, v1
	ds_bpermute_b32 v5, v199, v4
	v_mbcnt_lo_u32_b32 v0, -1, 0
	v_mbcnt_hi_u32_b32 v0, -1, v0
	s_cbranch_scc1 .LBB0_1005
	v_readlane_b32 s4, v242, 0
	v_readlane_b32 s5, v242, 1
	s_mov_b64 s[0:1], s[4:5]
	v_mov_b32_e32 v6, s0
	v_mov_b32_e32 v7, s1
	v_ashrrev_i32_e32 v1, 31, v0
	v_lshl_add_u64 v[6:7], v[0:1], 2, v[6:7]
	v_mov_b32_e32 v1, v12
	s_nop 0
	v_mov_b32_e32 v6, v13
	v_lshl_add_u32 v0, v0, 2, 0
	v_add_u32_e32 v0, 0x1e000, v0
	v_readlane_b32 s6, v242, 2
	v_readlane_b32 s7, v242, 3
	v_readlane_b32 s8, v242, 4
	v_readlane_b32 s9, v242, 5
	v_readlane_b32 s10, v242, 6
	v_readlane_b32 s11, v242, 7
	s_waitcnt vmcnt(1)
	v_mul_f32_e32 v1, 0x3f24fd5c, v1
	s_waitcnt vmcnt(0)
	v_mul_f32_e32 v6, 0x3f24fd5c, v6
	ds_write2st64_b32 v0, v1, v6 offset1:1
